# final RMSNorm: sum-of-squares butterflies by DPP adds + permlane16/32 swaps instead of 12 ds_bpermute round trips (same pairing, bit-identical)
# baseline (speedup 1.0000x reference)
; __global__ void __launch_bounds__(512, 2) mk_fwd(Args a) {
;     ...
;             for (int m = m_lo; m < m_hi; m += 2 * m_st) {
;                 f32x4* xr0 = (f32x4*)(a.out + (size_t)m * D) + lane; f32x4* xr1 = (f32x4*)(a.out + (size_t)(m + m_st) * D) + lane; f32x4 v0[4], v1[4];
; #pragma unroll
;                 for (int j = 0; j < 4; ++j) { v0[j] = xr0[64 * j]; v1[j] = xr1[64 * j]; }
;                 float s0 = 0.f, s1 = 0.f;
; #pragma unroll
;                 for (int j = 0; j < 4; ++j) { s0 += (v0[j][0] * v0[j][0] + v0[j][1] * v0[j][1]) + (v0[j][2] * v0[j][2] + v0[j][3] * v0[j][3]);
;                                               s1 += (v1[j][0] * v1[j][0] + v1[j][1] * v1[j][1]) + (v1[j][2] * v1[j][2] + v1[j][3] * v1[j][3]); }
.LBB0_30:
	s_ashr_i32 s5, s4, 31
	s_lshl_b64 s[2:3], s[4:5], 12
	v_lshl_add_u64 v[52:53], v[50:51], 0, s[2:3]
	s_add_i32 s8, s4, s96
	global_load_dwordx4 v[42:45], v[52:53], off
	global_load_dwordx4 v[34:37], v[52:53], off offset:1024
	global_load_dwordx4 v[18:21], v[52:53], off offset:3072
	s_ashr_i32 s9, s8, 31
	global_load_dwordx4 v[26:29], v[52:53], off offset:2048
	s_lshl_b64 s[2:3], s[8:9], 12
	v_lshl_add_u64 v[54:55], v[50:51], 0, s[2:3]
	global_load_dwordx4 v[46:49], v[54:55], off
	global_load_dwordx4 v[38:41], v[54:55], off offset:1024
	global_load_dwordx4 v[22:25], v[54:55], off offset:3072
	global_load_dwordx4 v[30:33], v[54:55], off offset:2048
	s_waitcnt vmcnt(7)
	v_pk_mul_f32 v[62:63], v[44:45], v[44:45]
	v_pk_mul_f32 v[64:65], v[42:43], v[42:43]
	s_waitcnt vmcnt(6)
	v_pk_mul_f32 v[66:67], v[36:37], v[36:37]
	v_pk_mul_f32 v[68:69], v[34:35], v[34:35]
	v_pk_mov_b32 v[74:75], v[64:65], v[62:63] op_sel:[1,0]
	v_mov_b32_e32 v65, v63
	s_waitcnt vmcnt(3)
	v_pk_mul_f32 v[62:63], v[48:49], v[48:49]
	v_pk_mul_f32 v[76:77], v[46:47], v[46:47]
	v_pk_mov_b32 v[78:79], v[68:69], v[66:67] op_sel:[1,0]
	v_mov_b32_e32 v69, v67
	v_mul_f32_e32 v70, v27, v27
	v_mul_f32_e32 v72, v29, v29
	s_waitcnt vmcnt(2)
	v_pk_mul_f32 v[66:67], v[40:41], v[40:41]
	v_pk_mul_f32 v[80:81], v[38:39], v[38:39]
	v_pk_add_f32 v[64:65], v[74:75], v[64:65]
	v_pk_mov_b32 v[74:75], v[76:77], v[62:63] op_sel:[1,0]
	v_mov_b32_e32 v77, v63
	v_pk_add_f32 v[62:63], v[78:79], v[68:69]
	v_mul_f32_e32 v61, v18, v18
	v_mul_f32_e32 v83, v19, v19
	v_mul_f32_e32 v85, v20, v20
	v_mul_f32_e32 v86, v21, v21
	v_pk_fma_f32 v[70:71], v[26:27], v[26:27], v[70:71] op_sel_hi:[1,1,0]
	v_pk_fma_f32 v[72:73], v[28:29], v[28:29], v[72:73] op_sel_hi:[1,1,0]
	v_pk_mov_b32 v[68:69], v[80:81], v[66:67] op_sel:[1,0]
	v_mov_b32_e32 v81, v67
	v_pk_add_f32 v[64:65], v[64:65], v[64:65] op_sel:[0,1] op_sel_hi:[1,0]
	v_pk_add_f32 v[62:63], v[62:63], v[62:63] op_sel:[0,1] op_sel_hi:[1,0]
	s_waitcnt vmcnt(0)
; __device__ __forceinline__ float sx(float v, int mask, int lane) { return __int_as_float(__builtin_amdgcn_ds_bpermute((lane ^ mask) << 2, __float_as_int(v))); }
; __device__ __forceinline__ float wave_sum(float v, int lane) {
; #pragma unroll
;     for (int o = 1; o < 64; o <<= 1) v += sx(v, o, lane);
;     return v;
; }
; __global__ void __launch_bounds__(512, 2) mk_fwd(Args a) {
;     ...
;                 s0 = wave_sum(s0, lane); s1 = wave_sum(s1, lane);
;                 const float rs0 = 1.0f / sqrtf(s0 * (1.0f / D) + RMS_EPS), rs1 = 1.0f / sqrtf(s1 * (1.0f / D) + RMS_EPS);
; #pragma unroll
;                 for (int j = 0; j < 4; ++j) { xr0[64 * j] = v0[j] * rs0 * gg[j]; xr1[64 * j] = v1[j] * rs1 * gg[j]; }
	v_mul_f32_e32 v82, v31, v31
	v_mul_f32_e32 v84, v33, v33
	v_mov_b32_e32 v71, v85
	v_mov_b32_e32 v73, v86
	v_pk_add_f32 v[74:75], v[74:75], v[76:77]
	v_pk_add_f32 v[68:69], v[68:69], v[80:81]
	v_mov_b32_e32 v65, v61
	v_mov_b32_e32 v63, v83
	v_mul_f32_e32 v87, v22, v22
	v_mul_f32_e32 v88, v23, v23
	v_mul_f32_e32 v89, v24, v24
	v_mul_f32_e32 v90, v25, v25
	v_pk_fma_f32 v[66:67], v[30:31], v[30:31], v[82:83] op_sel_hi:[1,1,0]
	v_pk_fma_f32 v[78:79], v[32:33], v[32:33], v[84:85] op_sel_hi:[1,1,0]
	v_pk_add_f32 v[70:71], v[70:71], v[72:73]
	v_pk_add_f32 v[72:73], v[74:75], v[74:75] op_sel:[0,1] op_sel_hi:[1,0]
	v_pk_add_f32 v[68:69], v[68:69], v[68:69] op_sel:[0,1] op_sel_hi:[1,0]
	v_pk_add_f32 v[62:63], v[64:65], v[62:63]
	v_mov_b32_e32 v67, v89
	v_mov_b32_e32 v79, v90
	v_mov_b32_e32 v73, v87
	v_mov_b32_e32 v69, v88
	v_pk_add_f32 v[62:63], v[62:63], v[70:71]
	v_pk_add_f32 v[66:67], v[66:67], v[78:79]
	v_pk_add_f32 v[64:65], v[72:73], v[68:69]
	v_add_f32_e32 v61, v62, v63
	v_pk_add_f32 v[62:63], v[64:65], v[66:67]
	v_add_f32_e32 v62, v62, v63
	s_nop 1
	v_add_f32_dpp v61, v61, v61 quad_perm:[1,0,3,2] row_mask:0xf bank_mask:0xf
	v_add_f32_dpp v62, v62, v62 quad_perm:[1,0,3,2] row_mask:0xf bank_mask:0xf
	s_nop 0
	v_add_f32_dpp v61, v61, v61 quad_perm:[2,3,0,1] row_mask:0xf bank_mask:0xf
	v_add_f32_dpp v62, v62, v62 quad_perm:[2,3,0,1] row_mask:0xf bank_mask:0xf
	s_nop 0
	v_add_f32_dpp v61, v61, v61 row_half_mirror row_mask:0xf bank_mask:0xf
	v_add_f32_dpp v62, v62, v62 row_half_mirror row_mask:0xf bank_mask:0xf
	s_nop 0
	v_add_f32_dpp v61, v61, v61 row_mirror row_mask:0xf bank_mask:0xf
	v_add_f32_dpp v62, v62, v62 row_mirror row_mask:0xf bank_mask:0xf
	v_mov_b32_e32 v64, v61
	v_mov_b32_e32 v63, v62
	s_nop 1
	v_permlane16_swap_b32_e32 v64, v61
	v_permlane16_swap_b32_e32 v63, v62
	v_add_f32_e32 v61, v61, v64
	v_add_f32_e32 v62, v62, v63
	v_mov_b32_e32 v64, v61
	v_mov_b32_e32 v63, v62
	s_nop 1
	v_permlane32_swap_b32_e32 v64, v61
	v_permlane32_swap_b32_e32 v63, v62
	v_add_f32_e32 v61, v61, v64
	v_fmamk_f32 v61, v61, 0x3a800000, v215
	v_add_f32_e32 v62, v62, v63
	v_mul_f32_e32 v63, 0x4f800000, v61
	v_cmp_gt_f32_e32 vcc, s10, v61
	v_fmamk_f32 v62, v62, 0x3a800000, v215
	v_cmp_gt_f32_e64 s[4:5], s10, v62
	v_cndmask_b32_e32 v61, v61, v63, vcc
	v_mul_f32_e32 v63, 0x4f800000, v62
	v_sqrt_f32_e32 v64, v61
	v_cndmask_b32_e64 v62, v62, v63, s[4:5]
	v_sqrt_f32_e32 v63, v62
	v_add_u32_e32 v65, -1, v64
	v_add_u32_e32 v66, 1, v64
	v_fma_f32 v67, -v65, v64, v61
	v_fma_f32 v68, -v66, v64, v61
	v_add_u32_e32 v69, -1, v63
	v_cmp_ge_f32_e64 s[6:7], 0, v67
	v_add_u32_e32 v70, 1, v63
	v_fma_f32 v67, -v70, v63, v62
	v_cndmask_b32_e64 v64, v64, v65, s[6:7]
	v_fma_f32 v65, -v69, v63, v62
	v_cmp_lt_f32_e64 s[6:7], 0, v68
	s_nop 1
	v_cndmask_b32_e64 v64, v64, v66, s[6:7]
	v_cmp_ge_f32_e64 s[6:7], 0, v65
	v_mul_f32_e32 v65, 0x37800000, v64
	v_cndmask_b32_e32 v64, v64, v65, vcc
	v_cndmask_b32_e64 v63, v63, v69, s[6:7]
	v_cmp_lt_f32_e64 s[6:7], 0, v67
	v_cmp_class_f32_e32 vcc, v61, v216
	s_nop 0
	v_cndmask_b32_e64 v63, v63, v70, s[6:7]
	v_mul_f32_e32 v65, 0x37800000, v63
	v_cndmask_b32_e32 v61, v64, v61, vcc
	v_cndmask_b32_e64 v63, v63, v65, s[4:5]
	v_div_scale_f32 v64, s[2:3], v61, v61, 1.0
	v_cmp_class_f32_e64 s[4:5], v62, v216
	v_div_scale_f32 v65, vcc, 1.0, v61, 1.0
	s_nop 0
	v_cndmask_b32_e64 v63, v63, v62, s[4:5]
	v_rcp_f32_e32 v62, v64
	v_div_scale_f32 v66, s[2:3], v63, v63, 1.0
	v_rcp_f32_e32 v67, v66
	v_fma_f32 v69, -v64, v62, 1.0
	v_fmac_f32_e32 v62, v69, v62
	v_mul_f32_e32 v70, v65, v62
	v_fma_f32 v69, -v66, v67, 1.0
	v_div_scale_f32 v68, s[4:5], 1.0, v63, 1.0
	v_fmac_f32_e32 v67, v69, v67
	v_fma_f32 v69, -v64, v70, v65
	v_mul_f32_e32 v71, v68, v67
	v_fmac_f32_e32 v70, v69, v62
	v_fma_f32 v69, -v66, v71, v68
	v_fma_f32 v64, -v64, v70, v65
	v_fmac_f32_e32 v71, v69, v67
	v_div_fmas_f32 v62, v64, v62, v70
	v_fma_f32 v64, -v66, v71, v68
	v_div_fixup_f32 v62, v62, v61, 1.0
	s_mov_b64 vcc, s[4:5]
	v_div_fmas_f32 v61, v64, v67, v71
	v_pk_mul_f32 v[42:43], v[62:63], v[42:43] op_sel_hi:[0,1]
	v_pk_mul_f32 v[44:45], v[62:63], v[44:45] op_sel_hi:[0,1]
	v_pk_mul_f32 v[34:35], v[62:63], v[34:35] op_sel_hi:[0,1]
	v_pk_mul_f32 v[36:37], v[62:63], v[36:37] op_sel_hi:[0,1]
	v_pk_mul_f32 v[26:27], v[62:63], v[26:27] op_sel_hi:[0,1]
	v_pk_mul_f32 v[28:29], v[62:63], v[28:29] op_sel_hi:[0,1]
	v_pk_mul_f32 v[18:19], v[62:63], v[18:19] op_sel_hi:[0,1]
	v_pk_mul_f32 v[20:21], v[62:63], v[20:21] op_sel_hi:[0,1]
	v_div_fixup_f32 v64, v61, v63, 1.0
	v_pk_mul_f32 v[44:45], v[44:45], v[4:5]
	v_pk_mul_f32 v[42:43], v[42:43], v[2:3]
	v_pk_mul_f32 v[36:37], v[36:37], v[8:9]
	v_pk_mul_f32 v[34:35], v[34:35], v[6:7]
	v_pk_mul_f32 v[28:29], v[28:29], v[12:13]
	v_pk_mul_f32 v[26:27], v[26:27], v[10:11]
	v_pk_mul_f32 v[20:21], v[20:21], v[16:17]
	v_pk_mul_f32 v[18:19], v[18:19], v[14:15]
	global_store_dwordx4 v[52:53], v[42:45], off
	global_store_dwordx4 v[52:53], v[34:37], off offset:1024
	global_store_dwordx4 v[52:53], v[26:29], off offset:2048
	v_pk_mul_f32 v[42:43], v[64:65], v[46:47] op_sel_hi:[0,1]
	v_pk_mul_f32 v[44:45], v[64:65], v[48:49] op_sel_hi:[0,1]
	v_pk_mul_f32 v[34:35], v[64:65], v[38:39] op_sel_hi:[0,1]
	v_pk_mul_f32 v[36:37], v[64:65], v[40:41] op_sel_hi:[0,1]
	v_pk_mul_f32 v[26:27], v[64:65], v[30:31] op_sel_hi:[0,1]
	v_pk_mul_f32 v[28:29], v[64:65], v[32:33] op_sel_hi:[0,1]
	global_store_dwordx4 v[52:53], v[18:21], off offset:3072
	s_add_i32 s4, s8, s96
	v_pk_mul_f32 v[44:45], v[4:5], v[44:45]
	v_pk_mul_f32 v[18:19], v[64:65], v[22:23] op_sel_hi:[0,1]
	v_pk_mul_f32 v[20:21], v[64:65], v[24:25] op_sel_hi:[0,1]
	v_pk_mul_f32 v[42:43], v[2:3], v[42:43]
	v_pk_mul_f32 v[36:37], v[8:9], v[36:37]
	v_pk_mul_f32 v[34:35], v[6:7], v[34:35]
	v_pk_mul_f32 v[28:29], v[12:13], v[28:29]
	v_pk_mul_f32 v[26:27], v[10:11], v[26:27]
	v_pk_mul_f32 v[20:21], v[16:17], v[20:21]
	v_pk_mul_f32 v[18:19], v[14:15], v[18:19]
	s_cmp_ge_i32 s4, s97
	global_store_dwordx4 v[54:55], v[42:45], off
	global_store_dwordx4 v[54:55], v[34:37], off offset:1024
	global_store_dwordx4 v[54:55], v[26:29], off offset:2048
	global_store_dwordx4 v[54:55], v[18:21], off offset:3072
	s_cbranch_scc0 .LBB0_30
